# GEMM K-loop: B0 fragment LDS reads moved into the read-free stage segments (8/4/8/4 balance), vmcnt guards added
# speedup vs baseline: 1.0032x; 1.0032x over previous
.LBB0_374:
	v_mov_b32_e32 v127, 0
	s_andn2_b64 vcc, exec, s[38:39]
	v_mov_b32_e32 v126, v127
	v_mov_b32_e32 v125, v127
	v_mov_b32_e32 v124, v127
	v_mov_b32_e32 v131, v127
	v_mov_b32_e32 v130, v127
	v_mov_b32_e32 v129, v127
	v_mov_b32_e32 v128, v127
	v_mov_b32_e32 v111, v127
	v_mov_b32_e32 v110, v127
	v_mov_b32_e32 v109, v127
	v_mov_b32_e32 v108, v127
	v_mov_b32_e32 v115, v127
	v_mov_b32_e32 v114, v127
	v_mov_b32_e32 v113, v127
	v_mov_b32_e32 v112, v127
	v_mov_b32_e32 v95, v127
	v_mov_b32_e32 v94, v127
	v_mov_b32_e32 v93, v127
	v_mov_b32_e32 v92, v127
	v_mov_b32_e32 v99, v127
	v_mov_b32_e32 v98, v127
	v_mov_b32_e32 v97, v127
	v_mov_b32_e32 v96, v127
	v_mov_b32_e32 v79, v127
	v_mov_b32_e32 v78, v127
	v_mov_b32_e32 v77, v127
	v_mov_b32_e32 v76, v127
	v_mov_b32_e32 v83, v127
	v_mov_b32_e32 v82, v127
	v_mov_b32_e32 v81, v127
	v_mov_b32_e32 v80, v127
	v_mov_b32_e32 v119, v127
	v_mov_b32_e32 v118, v127
	v_mov_b32_e32 v117, v127
	v_mov_b32_e32 v116, v127
	v_mov_b32_e32 v123, v127
	v_mov_b32_e32 v122, v127
	v_mov_b32_e32 v121, v127
	v_mov_b32_e32 v120, v127
	v_mov_b32_e32 v103, v127
	v_mov_b32_e32 v102, v127
	v_mov_b32_e32 v101, v127
	v_mov_b32_e32 v100, v127
	v_mov_b32_e32 v107, v127
	v_mov_b32_e32 v106, v127
	v_mov_b32_e32 v105, v127
	v_mov_b32_e32 v104, v127
	v_mov_b32_e32 v87, v127
	v_mov_b32_e32 v86, v127
	v_mov_b32_e32 v85, v127
	v_mov_b32_e32 v84, v127
	v_mov_b32_e32 v91, v127
	v_mov_b32_e32 v90, v127
	v_mov_b32_e32 v89, v127
	v_mov_b32_e32 v88, v127
	v_mov_b32_e32 v71, v127
	v_mov_b32_e32 v70, v127
	v_mov_b32_e32 v69, v127
	v_mov_b32_e32 v68, v127
	v_mov_b32_e32 v75, v127
	v_mov_b32_e32 v74, v127
	v_mov_b32_e32 v73, v127
	v_mov_b32_e32 v72, v127
	v_mov_b32_e32 v63, v127
	v_mov_b32_e32 v62, v127
	v_mov_b32_e32 v61, v127
	v_mov_b32_e32 v60, v127
	v_mov_b32_e32 v67, v127
	v_mov_b32_e32 v66, v127
	v_mov_b32_e32 v65, v127
	v_mov_b32_e32 v64, v127
	v_mov_b32_e32 v47, v127
	v_mov_b32_e32 v46, v127
	v_mov_b32_e32 v45, v127
	v_mov_b32_e32 v44, v127
	v_mov_b32_e32 v51, v127
	v_mov_b32_e32 v50, v127
	v_mov_b32_e32 v49, v127
	v_mov_b32_e32 v48, v127
	v_mov_b32_e32 v31, v127
	v_mov_b32_e32 v30, v127
	v_mov_b32_e32 v29, v127
	v_mov_b32_e32 v28, v127
	v_mov_b32_e32 v35, v127
	v_mov_b32_e32 v34, v127
	v_mov_b32_e32 v33, v127
	v_mov_b32_e32 v32, v127
	v_mov_b32_e32 v15, v127
	v_mov_b32_e32 v14, v127
	v_mov_b32_e32 v13, v127
	v_mov_b32_e32 v12, v127
	v_mov_b32_e32 v19, v127
	v_mov_b32_e32 v18, v127
	v_mov_b32_e32 v17, v127
	v_mov_b32_e32 v16, v127
	v_mov_b32_e32 v55, v127
	v_mov_b32_e32 v54, v127
	v_mov_b32_e32 v53, v127
	v_mov_b32_e32 v52, v127
	v_mov_b32_e32 v59, v127
	v_mov_b32_e32 v58, v127
	v_mov_b32_e32 v57, v127
	v_mov_b32_e32 v56, v127
	v_mov_b32_e32 v39, v127
	v_mov_b32_e32 v38, v127
	v_mov_b32_e32 v37, v127
	v_mov_b32_e32 v36, v127
	v_mov_b32_e32 v43, v127
	v_mov_b32_e32 v42, v127
	v_mov_b32_e32 v41, v127
	v_mov_b32_e32 v40, v127
	v_mov_b32_e32 v23, v127
	v_mov_b32_e32 v22, v127
	v_mov_b32_e32 v21, v127
	v_mov_b32_e32 v20, v127
	v_mov_b32_e32 v27, v127
	v_mov_b32_e32 v26, v127
	v_mov_b32_e32 v25, v127
	v_mov_b32_e32 v24, v127
	v_mov_b32_e32 v11, v127
	v_mov_b32_e32 v10, v127
	v_mov_b32_e32 v9, v127
	v_mov_b32_e32 v8, v127
	v_mov_b32_e32 v7, v127
	v_mov_b32_e32 v6, v127
	v_mov_b32_e32 v5, v127
	v_mov_b32_e32 v4, v127
	s_cbranch_vccnz .LBB0_377
	s_add_u32 s4, s4, 0x80
	s_addc_u32 s5, s5, 0
	s_add_u32 s1, s10, 0x100
	v_mov_b32_e32 v4, 0
	s_addc_u32 vcc_lo, s11, 0
	s_mov_b32 s10, 0
	v_mov_b32_e32 v5, v4
	v_mov_b32_e32 v6, v4
	v_mov_b32_e32 v7, v4
	v_mov_b32_e32 v8, v4
	v_mov_b32_e32 v9, v4
	v_mov_b32_e32 v10, v4
	v_mov_b32_e32 v11, v4
	v_mov_b32_e32 v24, v4
	v_mov_b32_e32 v25, v4
	v_mov_b32_e32 v26, v4
	v_mov_b32_e32 v27, v4
	v_mov_b32_e32 v20, v4
	v_mov_b32_e32 v21, v4
	v_mov_b32_e32 v22, v4
	v_mov_b32_e32 v23, v4
	v_mov_b32_e32 v40, v4
	v_mov_b32_e32 v41, v4
	v_mov_b32_e32 v42, v4
	v_mov_b32_e32 v43, v4
	v_mov_b32_e32 v36, v4
	v_mov_b32_e32 v37, v4
	v_mov_b32_e32 v38, v4
	v_mov_b32_e32 v39, v4
	v_mov_b32_e32 v56, v4
	v_mov_b32_e32 v57, v4
	v_mov_b32_e32 v58, v4
	v_mov_b32_e32 v59, v4
	v_mov_b32_e32 v52, v4
	v_mov_b32_e32 v53, v4
	v_mov_b32_e32 v54, v4
	v_mov_b32_e32 v55, v4
	v_mov_b32_e32 v16, v4
	v_mov_b32_e32 v17, v4
	v_mov_b32_e32 v18, v4
	v_mov_b32_e32 v19, v4
	v_mov_b32_e32 v12, v4
	v_mov_b32_e32 v13, v4
	v_mov_b32_e32 v14, v4
	v_mov_b32_e32 v15, v4
	v_mov_b32_e32 v32, v4
	v_mov_b32_e32 v33, v4
	v_mov_b32_e32 v34, v4
	v_mov_b32_e32 v35, v4
	v_mov_b32_e32 v28, v4
	v_mov_b32_e32 v29, v4
	v_mov_b32_e32 v30, v4
	v_mov_b32_e32 v31, v4
	v_mov_b32_e32 v48, v4
	v_mov_b32_e32 v49, v4
	v_mov_b32_e32 v50, v4
	v_mov_b32_e32 v51, v4
	v_mov_b32_e32 v44, v4
	v_mov_b32_e32 v45, v4
	v_mov_b32_e32 v46, v4
	v_mov_b32_e32 v47, v4
	v_mov_b32_e32 v64, v4
	v_mov_b32_e32 v65, v4
	v_mov_b32_e32 v66, v4
	v_mov_b32_e32 v67, v4
	v_mov_b32_e32 v60, v4
	v_mov_b32_e32 v61, v4
	v_mov_b32_e32 v62, v4
	v_mov_b32_e32 v63, v4
	v_mov_b32_e32 v72, v4
	v_mov_b32_e32 v73, v4
	v_mov_b32_e32 v74, v4
	v_mov_b32_e32 v75, v4
	v_mov_b32_e32 v68, v4
	v_mov_b32_e32 v69, v4
	v_mov_b32_e32 v70, v4
	v_mov_b32_e32 v71, v4
	v_mov_b32_e32 v88, v4
	v_mov_b32_e32 v89, v4
	v_mov_b32_e32 v90, v4
	v_mov_b32_e32 v91, v4
	v_mov_b32_e32 v84, v4
	v_mov_b32_e32 v85, v4
	v_mov_b32_e32 v86, v4
	v_mov_b32_e32 v87, v4
	v_mov_b32_e32 v104, v4
	v_mov_b32_e32 v105, v4
	v_mov_b32_e32 v106, v4
	v_mov_b32_e32 v107, v4
	v_mov_b32_e32 v100, v4
	v_mov_b32_e32 v101, v4
	v_mov_b32_e32 v102, v4
	v_mov_b32_e32 v103, v4
	v_mov_b32_e32 v120, v4
	v_mov_b32_e32 v121, v4
	v_mov_b32_e32 v122, v4
	v_mov_b32_e32 v123, v4
	v_mov_b32_e32 v116, v4
	v_mov_b32_e32 v117, v4
	v_mov_b32_e32 v118, v4
	v_mov_b32_e32 v119, v4
	v_mov_b32_e32 v80, v4
	v_mov_b32_e32 v81, v4
	v_mov_b32_e32 v82, v4
	v_mov_b32_e32 v83, v4
	v_mov_b32_e32 v76, v4
	v_mov_b32_e32 v77, v4
	v_mov_b32_e32 v78, v4
	v_mov_b32_e32 v79, v4
	v_mov_b32_e32 v96, v4
	v_mov_b32_e32 v97, v4
	v_mov_b32_e32 v98, v4
	v_mov_b32_e32 v99, v4
	v_mov_b32_e32 v92, v4
	v_mov_b32_e32 v93, v4
	v_mov_b32_e32 v94, v4
	v_mov_b32_e32 v95, v4
	v_mov_b32_e32 v112, v4
	v_mov_b32_e32 v113, v4
	v_mov_b32_e32 v114, v4
	v_mov_b32_e32 v115, v4
	v_mov_b32_e32 v108, v4
	v_mov_b32_e32 v109, v4
	v_mov_b32_e32 v110, v4
	v_mov_b32_e32 v111, v4
	v_mov_b32_e32 v128, v4
	v_mov_b32_e32 v129, v4
	v_mov_b32_e32 v130, v4
	v_mov_b32_e32 v131, v4
	v_mov_b32_e32 v124, v4
	v_mov_b32_e32 v125, v4
	v_mov_b32_e32 v126, v4
	v_mov_b32_e32 v127, v4
	v_add_u32_e32 v1, 0x10000, v238
	ds_read_b128 v[132:135], v1
	ds_read_b128 v[136:139], v1 offset:1024
	ds_read_b128 v[140:143], v1 offset:2048
	ds_read_b128 v[144:147], v1 offset:3072
.LBB0_376:
	s_add_i32 vcc_hi, s10, 2
	s_add_u32 s56, s4, 0x80
	s_addc_u32 s11, s5, 0
	s_add_i32 s98, 0, 0x10000
	v_add_u32_e32 v1, s98, v238
	s_cmp_eq_u32 s75, s10
	s_cselect_b32 s10, s50, s56
	s_cselect_b32 s11, s51, s11
	s_cselect_b32 s57, s97, vcc_lo
	s_cselect_b32 s56, s96, s1
	v_lshl_add_u64 v[180:181], s[4:5], 0, v[206:207]
	s_add_i32 m0, s73, 0xc000
	ds_read_b128 v[148:151], v240
	ds_read_b128 v[152:155], v240 offset:1024
	ds_read_b128 v[156:159], v240 offset:2048
	ds_read_b128 v[160:163], v240 offset:3072
	ds_read_b128 v[164:167], v240 offset:4096
	ds_read_b128 v[168:171], v240 offset:5120
	ds_read_b128 v[172:175], v240 offset:6144
	ds_read_b128 v[176:179], v240 offset:7168
	global_load_lds_dwordx4 v[180:181], off
	v_lshl_add_u64 v[180:181], s[4:5], 0, v[208:209]
	s_add_i32 m0, s73, 0xe000
	s_nop 0
	global_load_lds_dwordx4 v[180:181], off
	s_waitcnt lgkmcnt(8)
	s_waitcnt vmcnt(10)
	s_barrier
	s_waitcnt lgkmcnt(0)
	s_setprio 1
	s_waitcnt lgkmcnt(0)
	v_mfma_f32_16x16x32_f16 v[124:127], v[132:135], v[148:151], v[124:127]
	v_mfma_f32_16x16x32_f16 v[128:131], v[140:143], v[148:151], v[128:131]
	v_mfma_f32_16x16x32_f16 v[108:111], v[132:135], v[156:159], v[108:111]
	v_mfma_f32_16x16x32_f16 v[112:115], v[140:143], v[156:159], v[112:115]
	v_mfma_f32_16x16x32_f16 v[92:95], v[132:135], v[164:167], v[92:95]
	v_mfma_f32_16x16x32_f16 v[96:99], v[140:143], v[164:167], v[96:99]
	v_mfma_f32_16x16x32_f16 v[76:79], v[132:135], v[172:175], v[76:79]
	v_mfma_f32_16x16x32_f16 v[80:83], v[140:143], v[172:175], v[80:83]
	v_mfma_f32_16x16x32_f16 v[124:127], v[136:139], v[152:155], v[124:127]
	v_mfma_f32_16x16x32_f16 v[128:131], v[144:147], v[152:155], v[128:131]
	v_mfma_f32_16x16x32_f16 v[108:111], v[136:139], v[160:163], v[108:111]
	v_mfma_f32_16x16x32_f16 v[112:115], v[144:147], v[160:163], v[112:115]
	v_mfma_f32_16x16x32_f16 v[92:95], v[136:139], v[168:171], v[92:95]
	v_mfma_f32_16x16x32_f16 v[96:99], v[144:147], v[168:171], v[96:99]
	v_mfma_f32_16x16x32_f16 v[76:79], v[136:139], v[176:179], v[76:79]
	v_mfma_f32_16x16x32_f16 v[80:83], v[144:147], v[176:179], v[80:83]
	s_setprio 0
	s_barrier
	s_add_i32 s98, s98, s72
	v_add_u32_e32 v1, s58, v238
	v_lshl_add_u64 v[210:211], s[56:57], 0, v[200:201]
	s_mov_b32 m0, s98
	ds_read_b128 v[180:183], v1
	ds_read_b128 v[184:187], v1 offset:1024
	ds_read_b128 v[188:191], v1 offset:2048
	ds_read_b128 v[192:195], v1 offset:3072
	global_load_lds_dwordx4 v[210:211], off
	v_lshl_add_u64 v[212:213], s[56:57], 0, v[202:203]
	s_add_i32 m0, s98, 0x2000
	s_nop 0
	global_load_lds_dwordx4 v[212:213], off
	s_waitcnt vmcnt(10)
	s_barrier
	s_waitcnt lgkmcnt(0)
	s_setprio 1
	s_waitcnt lgkmcnt(0)
	v_mfma_f32_16x16x32_f16 v[116:119], v[180:183], v[148:151], v[116:119]
	v_mfma_f32_16x16x32_f16 v[120:123], v[188:191], v[148:151], v[120:123]
	v_mfma_f32_16x16x32_f16 v[100:103], v[180:183], v[156:159], v[100:103]
	v_mfma_f32_16x16x32_f16 v[104:107], v[188:191], v[156:159], v[104:107]
	v_mfma_f32_16x16x32_f16 v[84:87], v[180:183], v[164:167], v[84:87]
	v_mfma_f32_16x16x32_f16 v[88:91], v[188:191], v[164:167], v[88:91]
	v_mfma_f32_16x16x32_f16 v[68:71], v[180:183], v[172:175], v[68:71]
	v_mfma_f32_16x16x32_f16 v[72:75], v[188:191], v[172:175], v[72:75]
	v_mfma_f32_16x16x32_f16 v[116:119], v[184:187], v[152:155], v[116:119]
	v_mfma_f32_16x16x32_f16 v[120:123], v[192:195], v[152:155], v[120:123]
	v_mfma_f32_16x16x32_f16 v[100:103], v[184:187], v[160:163], v[100:103]
	v_mfma_f32_16x16x32_f16 v[104:107], v[192:195], v[160:163], v[104:107]
	v_mfma_f32_16x16x32_f16 v[84:87], v[184:187], v[168:171], v[84:87]
	v_mfma_f32_16x16x32_f16 v[88:91], v[192:195], v[168:171], v[88:91]
	v_mfma_f32_16x16x32_f16 v[68:71], v[184:187], v[176:179], v[68:71]
	v_mfma_f32_16x16x32_f16 v[72:75], v[192:195], v[176:179], v[72:75]
	s_setprio 0
	s_mov_b32 m0, s73
	v_lshl_add_u64 v[214:215], s[10:11], 0, v[200:201]
	s_barrier
	ds_read_b128 v[148:151], v240 offset:16384
	ds_read_b128 v[152:155], v240 offset:17408
	ds_read_b128 v[156:159], v240 offset:18432
	ds_read_b128 v[160:163], v240 offset:19456
	ds_read_b128 v[164:167], v240 offset:20480
	ds_read_b128 v[168:171], v240 offset:21504
	ds_read_b128 v[172:175], v240 offset:22528
	ds_read_b128 v[176:179], v240 offset:23552
	global_load_lds_dwordx4 v[214:215], off
	v_lshl_add_u64 v[216:217], s[10:11], 0, v[202:203]
	s_mov_b32 m0, s78
	s_nop 0
	global_load_lds_dwordx4 v[216:217], off
	s_waitcnt vmcnt(10)
	s_barrier
	s_waitcnt lgkmcnt(0)
	s_setprio 1
	s_waitcnt lgkmcnt(0)
	v_mfma_f32_16x16x32_f16 v[60:63], v[132:135], v[148:151], v[60:63]
	v_mfma_f32_16x16x32_f16 v[64:67], v[140:143], v[148:151], v[64:67]
	v_mfma_f32_16x16x32_f16 v[44:47], v[132:135], v[156:159], v[44:47]
	v_mfma_f32_16x16x32_f16 v[48:51], v[140:143], v[156:159], v[48:51]
	v_mfma_f32_16x16x32_f16 v[28:31], v[132:135], v[164:167], v[28:31]
	v_mfma_f32_16x16x32_f16 v[32:35], v[140:143], v[164:167], v[32:35]
	v_mfma_f32_16x16x32_f16 v[12:15], v[132:135], v[172:175], v[12:15]
	v_mfma_f32_16x16x32_f16 v[16:19], v[140:143], v[172:175], v[16:19]
	v_mfma_f32_16x16x32_f16 v[60:63], v[136:139], v[152:155], v[60:63]
	v_mfma_f32_16x16x32_f16 v[64:67], v[144:147], v[152:155], v[64:67]
	v_mfma_f32_16x16x32_f16 v[44:47], v[136:139], v[160:163], v[44:47]
	v_mfma_f32_16x16x32_f16 v[48:51], v[144:147], v[160:163], v[48:51]
	v_mfma_f32_16x16x32_f16 v[28:31], v[136:139], v[168:171], v[28:31]
	v_mfma_f32_16x16x32_f16 v[32:35], v[144:147], v[168:171], v[32:35]
	v_mfma_f32_16x16x32_f16 v[12:15], v[136:139], v[176:179], v[12:15]
	v_mfma_f32_16x16x32_f16 v[16:19], v[144:147], v[176:179], v[16:19]
	s_setprio 0
	s_barrier
	v_add_u32_e32 v1, s99, v238
	ds_read_b128 v[132:135], v1
	ds_read_b128 v[136:139], v1 offset:1024
	ds_read_b128 v[140:143], v1 offset:2048
	ds_read_b128 v[144:147], v1 offset:3072
	s_add_u32 s56, s56, s28
	s_addc_u32 s57, s57, s29
	s_add_i32 s98, s58, s72
	v_lshl_add_u64 v[218:219], s[56:57], 0, v[200:201]
	s_mov_b32 m0, s98
	v_lshl_add_u64 v[220:221], s[56:57], 0, v[202:203]
	global_load_lds_dwordx4 v[218:219], off
	s_add_i32 m0, s98, 0x2000
	s_nop 0
	global_load_lds_dwordx4 v[220:221], off
	s_waitcnt vmcnt(10)
	s_barrier
	s_setprio 1
	v_mfma_f32_16x16x32_f16 v[52:55], v[180:183], v[148:151], v[52:55]
	v_mfma_f32_16x16x32_f16 v[56:59], v[188:191], v[148:151], v[56:59]
	v_mfma_f32_16x16x32_f16 v[36:39], v[180:183], v[156:159], v[36:39]
	v_mfma_f32_16x16x32_f16 v[40:43], v[188:191], v[156:159], v[40:43]
	v_mfma_f32_16x16x32_f16 v[20:23], v[180:183], v[164:167], v[20:23]
	v_mfma_f32_16x16x32_f16 v[24:27], v[188:191], v[164:167], v[24:27]
	v_mfma_f32_16x16x32_f16 v[8:11], v[180:183], v[172:175], v[8:11]
	v_mfma_f32_16x16x32_f16 v[4:7], v[188:191], v[172:175], v[4:7]
	v_mfma_f32_16x16x32_f16 v[52:55], v[184:187], v[152:155], v[52:55]
	v_mfma_f32_16x16x32_f16 v[56:59], v[192:195], v[152:155], v[56:59]
	v_mfma_f32_16x16x32_f16 v[36:39], v[184:187], v[160:163], v[36:39]
	v_mfma_f32_16x16x32_f16 v[40:43], v[192:195], v[160:163], v[40:43]
	v_mfma_f32_16x16x32_f16 v[20:23], v[184:187], v[168:171], v[20:23]
	v_mfma_f32_16x16x32_f16 v[24:27], v[192:195], v[168:171], v[24:27]
	v_mfma_f32_16x16x32_f16 v[8:11], v[184:187], v[176:179], v[8:11]
	v_mfma_f32_16x16x32_f16 v[4:7], v[192:195], v[176:179], v[4:7]
	s_setprio 0
	v_add_u32_e32 v1, s99, v238
	s_barrier
	s_add_u32 s10, s10, s28
	s_addc_u32 s11, s11, s29
	s_mov_b32 m0, s79
	v_lshl_add_u64 v[180:181], s[10:11], 0, v[200:201]
	ds_read_b128 v[148:151], v240 offset:32768
	ds_read_b128 v[152:155], v240 offset:33792
	ds_read_b128 v[156:159], v240 offset:34816
	ds_read_b128 v[160:163], v240 offset:35840
	ds_read_b128 v[164:167], v240 offset:36864
	ds_read_b128 v[168:171], v240 offset:37888
	ds_read_b128 v[172:175], v240 offset:38912
	ds_read_b128 v[176:179], v240 offset:39936
	global_load_lds_dwordx4 v[180:181], off
	v_lshl_add_u64 v[180:181], s[10:11], 0, v[202:203]
	s_mov_b32 m0, s60
	s_nop 0
	global_load_lds_dwordx4 v[180:181], off
	s_waitcnt lgkmcnt(8)
	s_waitcnt vmcnt(10)
	s_barrier
	s_waitcnt lgkmcnt(0)
	s_setprio 1
	s_waitcnt lgkmcnt(0)
	v_mfma_f32_16x16x32_f16 v[124:127], v[132:135], v[148:151], v[124:127]
	v_mfma_f32_16x16x32_f16 v[128:131], v[140:143], v[148:151], v[128:131]
	v_mfma_f32_16x16x32_f16 v[108:111], v[132:135], v[156:159], v[108:111]
	v_mfma_f32_16x16x32_f16 v[112:115], v[140:143], v[156:159], v[112:115]
	v_mfma_f32_16x16x32_f16 v[92:95], v[132:135], v[164:167], v[92:95]
	v_mfma_f32_16x16x32_f16 v[96:99], v[140:143], v[164:167], v[96:99]
	v_mfma_f32_16x16x32_f16 v[76:79], v[132:135], v[172:175], v[76:79]
	v_mfma_f32_16x16x32_f16 v[80:83], v[140:143], v[172:175], v[80:83]
	v_mfma_f32_16x16x32_f16 v[124:127], v[136:139], v[152:155], v[124:127]
	v_mfma_f32_16x16x32_f16 v[128:131], v[144:147], v[152:155], v[128:131]
	v_mfma_f32_16x16x32_f16 v[108:111], v[136:139], v[160:163], v[108:111]
	v_mfma_f32_16x16x32_f16 v[112:115], v[144:147], v[160:163], v[112:115]
	v_mfma_f32_16x16x32_f16 v[92:95], v[136:139], v[168:171], v[92:95]
	v_mfma_f32_16x16x32_f16 v[96:99], v[144:147], v[168:171], v[96:99]
	v_mfma_f32_16x16x32_f16 v[76:79], v[136:139], v[176:179], v[76:79]
	v_mfma_f32_16x16x32_f16 v[80:83], v[144:147], v[176:179], v[80:83]
	s_setprio 0
	s_barrier
	s_add_i32 s10, 0, 0x1c000
	s_add_i32 s11, s99, s72
	v_add_u32_e32 v1, s10, v238
	v_lshl_add_u64 v[210:211], v[210:211], 0, s[86:87]
	s_mov_b32 m0, s11
	ds_read_b128 v[180:183], v1
	ds_read_b128 v[184:187], v1 offset:1024
	ds_read_b128 v[188:191], v1 offset:2048
	ds_read_b128 v[192:195], v1 offset:3072
	global_load_lds_dwordx4 v[210:211], off
	v_lshl_add_u64 v[210:211], v[212:213], 0, s[86:87]
	s_add_i32 m0, s11, 0x2000
	s_nop 0
	global_load_lds_dwordx4 v[210:211], off
	s_waitcnt vmcnt(10)
	s_barrier
	s_waitcnt lgkmcnt(0)
	s_setprio 1
	s_waitcnt lgkmcnt(0)
	v_mfma_f32_16x16x32_f16 v[116:119], v[180:183], v[148:151], v[116:119]
	v_mfma_f32_16x16x32_f16 v[120:123], v[188:191], v[148:151], v[120:123]
	v_mfma_f32_16x16x32_f16 v[100:103], v[180:183], v[156:159], v[100:103]
	v_mfma_f32_16x16x32_f16 v[104:107], v[188:191], v[156:159], v[104:107]
	v_mfma_f32_16x16x32_f16 v[84:87], v[180:183], v[164:167], v[84:87]
	v_mfma_f32_16x16x32_f16 v[88:91], v[188:191], v[164:167], v[88:91]
	v_mfma_f32_16x16x32_f16 v[68:71], v[180:183], v[172:175], v[68:71]
	v_mfma_f32_16x16x32_f16 v[72:75], v[188:191], v[172:175], v[72:75]
	v_mfma_f32_16x16x32_f16 v[116:119], v[184:187], v[152:155], v[116:119]
	v_mfma_f32_16x16x32_f16 v[120:123], v[192:195], v[152:155], v[120:123]
	v_mfma_f32_16x16x32_f16 v[100:103], v[184:187], v[160:163], v[100:103]
	v_mfma_f32_16x16x32_f16 v[104:107], v[192:195], v[160:163], v[104:107]
	v_mfma_f32_16x16x32_f16 v[84:87], v[184:187], v[168:171], v[84:87]
	v_mfma_f32_16x16x32_f16 v[88:91], v[192:195], v[168:171], v[88:91]
	v_mfma_f32_16x16x32_f16 v[68:71], v[184:187], v[176:179], v[68:71]
	v_mfma_f32_16x16x32_f16 v[72:75], v[192:195], v[176:179], v[72:75]
	s_setprio 0
	s_mov_b32 m0, s77
	v_lshl_add_u64 v[210:211], v[214:215], 0, s[86:87]
	s_barrier
	ds_read_b128 v[148:151], v240 offset:49152
	ds_read_b128 v[152:155], v240 offset:50176
	ds_read_b128 v[156:159], v240 offset:51200
	ds_read_b128 v[160:163], v240 offset:52224
	ds_read_b128 v[164:167], v240 offset:53248
	ds_read_b128 v[168:171], v240 offset:54272
	ds_read_b128 v[172:175], v240 offset:55296
	ds_read_b128 v[176:179], v240 offset:56320
	global_load_lds_dwordx4 v[210:211], off
	v_lshl_add_u64 v[210:211], v[216:217], 0, s[86:87]
	s_mov_b32 m0, s64
	s_nop 0
	global_load_lds_dwordx4 v[210:211], off
	s_waitcnt vmcnt(10)
	s_barrier
	s_waitcnt lgkmcnt(0)
	s_setprio 1
	s_waitcnt lgkmcnt(0)
	v_mfma_f32_16x16x32_f16 v[60:63], v[132:135], v[148:151], v[60:63]
	v_mfma_f32_16x16x32_f16 v[64:67], v[140:143], v[148:151], v[64:67]
	v_mfma_f32_16x16x32_f16 v[44:47], v[132:135], v[156:159], v[44:47]
	v_mfma_f32_16x16x32_f16 v[48:51], v[140:143], v[156:159], v[48:51]
	v_mfma_f32_16x16x32_f16 v[28:31], v[132:135], v[164:167], v[28:31]
	v_mfma_f32_16x16x32_f16 v[32:35], v[140:143], v[164:167], v[32:35]
	v_mfma_f32_16x16x32_f16 v[12:15], v[132:135], v[172:175], v[12:15]
	v_mfma_f32_16x16x32_f16 v[16:19], v[140:143], v[172:175], v[16:19]
	v_mfma_f32_16x16x32_f16 v[60:63], v[136:139], v[152:155], v[60:63]
	v_mfma_f32_16x16x32_f16 v[64:67], v[144:147], v[152:155], v[64:67]
	v_mfma_f32_16x16x32_f16 v[44:47], v[136:139], v[160:163], v[44:47]
	v_mfma_f32_16x16x32_f16 v[48:51], v[144:147], v[160:163], v[48:51]
	v_mfma_f32_16x16x32_f16 v[28:31], v[136:139], v[168:171], v[28:31]
	v_mfma_f32_16x16x32_f16 v[32:35], v[144:147], v[168:171], v[32:35]
	v_mfma_f32_16x16x32_f16 v[12:15], v[136:139], v[176:179], v[12:15]
	v_mfma_f32_16x16x32_f16 v[16:19], v[144:147], v[176:179], v[16:19]
	s_setprio 0
	s_barrier
	v_add_u32_e32 v1, 0x10000, v238
	ds_read_b128 v[132:135], v1
	ds_read_b128 v[136:139], v1 offset:1024
	ds_read_b128 v[140:143], v1 offset:2048
	ds_read_b128 v[144:147], v1 offset:3072
	s_add_i32 s10, s10, s72
	v_lshl_add_u64 v[222:223], v[218:219], 0, s[86:87]
	s_mov_b32 m0, s10
	s_nop 0
	global_load_lds_dwordx4 v[222:223], off
	v_lshl_add_u64 v[222:223], v[220:221], 0, s[86:87]
	s_add_i32 m0, s10, 0x2000
	s_nop 0
	global_load_lds_dwordx4 v[222:223], off
	s_waitcnt vmcnt(10)
	s_barrier
	s_setprio 1
	v_mfma_f32_16x16x32_f16 v[52:55], v[180:183], v[148:151], v[52:55]
	v_mfma_f32_16x16x32_f16 v[56:59], v[188:191], v[148:151], v[56:59]
	v_mfma_f32_16x16x32_f16 v[36:39], v[180:183], v[156:159], v[36:39]
	v_mfma_f32_16x16x32_f16 v[40:43], v[188:191], v[156:159], v[40:43]
	v_mfma_f32_16x16x32_f16 v[20:23], v[180:183], v[164:167], v[20:23]
	v_mfma_f32_16x16x32_f16 v[24:27], v[188:191], v[164:167], v[24:27]
	v_mfma_f32_16x16x32_f16 v[8:11], v[180:183], v[172:175], v[8:11]
	v_mfma_f32_16x16x32_f16 v[4:7], v[188:191], v[172:175], v[4:7]
	v_mfma_f32_16x16x32_f16 v[52:55], v[184:187], v[152:155], v[52:55]
	v_mfma_f32_16x16x32_f16 v[56:59], v[192:195], v[152:155], v[56:59]
	v_mfma_f32_16x16x32_f16 v[36:39], v[184:187], v[160:163], v[36:39]
	v_mfma_f32_16x16x32_f16 v[40:43], v[192:195], v[160:163], v[40:43]
	v_mfma_f32_16x16x32_f16 v[20:23], v[184:187], v[168:171], v[20:23]
	v_mfma_f32_16x16x32_f16 v[24:27], v[192:195], v[168:171], v[24:27]
	v_mfma_f32_16x16x32_f16 v[8:11], v[184:187], v[176:179], v[8:11]
	v_mfma_f32_16x16x32_f16 v[4:7], v[192:195], v[176:179], v[4:7]
	s_setprio 0
	s_add_u32 s4, s4, 0x100
	s_addc_u32 s5, s5, 0
	s_add_u32 s1, s1, 0x100
	s_addc_u32 vcc_lo, vcc_lo, 0
	s_cmp_ge_i32 vcc_hi, s67
	s_mov_b32 s10, vcc_hi
	s_barrier
	s_cbranch_scc0 .LBB0_376
.LBB0_377:
	s_waitcnt lgkmcnt(0)
	s_lshl_b32 s1, s0, 8
	s_lshl_b32 s4, s71, 8
	s_mov_b64 s[10:11], -1
	s_and_b64 vcc, exec, s[40:41]
	s_cbranch_vccz .LBB0_453
	s_and_b64 vcc, exec, s[42:43]
	s_cbranch_vccz .LBB0_386
	s_and_b64 vcc, exec, s[48:49]
	s_cbranch_vccz .LBB0_381
	v_mul_f32_e32 v132, 0xbfb8aa3b, v124
	v_mul_f32_e32 v133, 0xbfb8aa3b, v125
	v_exp_f32_e32 v132, v132
	v_exp_f32_e32 v133, v133
	v_lshl_or_b32 v134, s71, 7, v239
	v_add_u32_e32 v1, s1, v199
	v_add_f32_e32 v132, 1.0, v132
	v_add_f32_e32 v133, 1.0, v133
	v_rcp_f32_e32 v132, v132
	v_rcp_f32_e32 v133, v133
	v_ashrrev_i32_e32 v135, 31, v134
	v_lshlrev_b64 v[134:135], 1, v[134:135]
	v_add_u32_e32 v142, 0x80, v1
	v_pk_mul_f32 v[132:133], v[124:125], v[132:133]
	s_nop 0
	v_pk_mul_f32 v[132:133], v[116:117], v[132:133]
	s_nop 0
	v_cvt_pk_f16_f32 v136, v132, v133
	v_mul_f32_e32 v132, 0xbfb8aa3b, v126
	v_mul_f32_e32 v133, 0xbfb8aa3b, v127
	v_exp_f32_e32 v132, v132
	v_exp_f32_e32 v133, v133
	v_add_f32_e32 v132, 1.0, v132
	v_add_f32_e32 v133, 1.0, v133
	v_rcp_f32_e32 v132, v132
	v_rcp_f32_e32 v133, v133
	s_nop 0
	v_pk_mul_f32 v[132:133], v[126:127], v[132:133]
	s_nop 0
	v_pk_mul_f32 v[132:133], v[118:119], v[132:133]
	s_nop 0
	v_cvt_pk_f16_f32 v137, v132, v133
	v_mul_f32_e32 v132, 0xbfb8aa3b, v128
	v_mul_f32_e32 v133, 0xbfb8aa3b, v129
	v_exp_f32_e32 v132, v132
	v_exp_f32_e32 v133, v133
	v_add_f32_e32 v132, 1.0, v132
	v_add_f32_e32 v133, 1.0, v133
	v_rcp_f32_e32 v132, v132
	v_rcp_f32_e32 v133, v133
	s_nop 0
	v_pk_mul_f32 v[132:133], v[128:129], v[132:133]
	s_nop 0
	v_pk_mul_f32 v[132:133], v[120:121], v[132:133]
	s_nop 0
	v_cvt_pk_f16_f32 v138, v132, v133
	v_mul_f32_e32 v132, 0xbfb8aa3b, v130
	v_mul_f32_e32 v133, 0xbfb8aa3b, v131
	v_exp_f32_e32 v132, v132
	v_exp_f32_e32 v133, v133
	v_add_f32_e32 v132, 1.0, v132
	v_add_f32_e32 v133, 1.0, v133
	v_rcp_f32_e32 v132, v132
	v_rcp_f32_e32 v133, v133
	s_nop 0
	v_pk_mul_f32 v[132:133], v[130:131], v[132:133]
	s_nop 0
	v_pk_mul_f32 v[132:133], v[122:123], v[132:133]
	s_nop 0
	v_cvt_pk_f16_f32 v139, v132, v133
	v_mov_b64_e32 v[132:133], s[34:35]
	v_mad_i64_i32 v[140:141], s[10:11], v1, s59, v[132:133]
	v_lshl_add_u64 v[140:141], v[140:141], 0, v[134:135]
	global_store_dwordx4 v[140:141], v[136:139], off
	s_nop 1
	v_mul_f32_e32 v136, 0xbfb8aa3b, v108
	v_mul_f32_e32 v137, 0xbfb8aa3b, v109
	v_exp_f32_e32 v136, v136
	v_exp_f32_e32 v137, v137
	v_add_f32_e32 v136, 1.0, v136
	v_add_f32_e32 v137, 1.0, v137
	v_rcp_f32_e32 v136, v136
	v_rcp_f32_e32 v137, v137
	s_nop 0
	v_pk_mul_f32 v[136:137], v[108:109], v[136:137]
	s_nop 0
	v_pk_mul_f32 v[136:137], v[100:101], v[136:137]
	s_nop 0
	v_cvt_pk_f16_f32 v136, v136, v137
	v_mul_f32_e32 v137, 0xbfb8aa3b, v110
	v_exp_f32_e32 v137, v137
	s_nop 0
	v_add_f32_e32 v137, 1.0, v137
	v_rcp_f32_e32 v138, v137
	v_mul_f32_e32 v137, 0xbfb8aa3b, v111
	v_exp_f32_e32 v137, v137
	s_nop 0
	v_add_f32_e32 v137, 1.0, v137
	v_rcp_f32_e32 v139, v137
	s_nop 0
	v_pk_mul_f32 v[138:139], v[110:111], v[138:139]
	s_nop 0
	v_pk_mul_f32 v[138:139], v[102:103], v[138:139]
	s_nop 0
	v_cvt_pk_f16_f32 v137, v138, v139
	v_mul_f32_e32 v138, 0xbfb8aa3b, v112
	v_mul_f32_e32 v139, 0xbfb8aa3b, v113
	v_exp_f32_e32 v138, v138
	v_exp_f32_e32 v139, v139
	v_add_f32_e32 v138, 1.0, v138
	v_add_f32_e32 v139, 1.0, v139
	v_rcp_f32_e32 v138, v138
	v_rcp_f32_e32 v139, v139
	s_nop 0
	v_pk_mul_f32 v[138:139], v[112:113], v[138:139]
	s_nop 0
	v_pk_mul_f32 v[138:139], v[104:105], v[138:139]
	s_nop 0
	v_cvt_pk_f16_f32 v138, v138, v139
	v_mul_f32_e32 v139, 0xbfb8aa3b, v114
	v_exp_f32_e32 v139, v139
	s_nop 0
	v_add_f32_e32 v139, 1.0, v139
	v_rcp_f32_e32 v140, v139
	v_mul_f32_e32 v139, 0xbfb8aa3b, v115
	v_exp_f32_e32 v139, v139
	s_nop 0
	v_add_f32_e32 v139, 1.0, v139
	v_rcp_f32_e32 v141, v139
	s_nop 0
	v_pk_mul_f32 v[140:141], v[114:115], v[140:141]
	s_nop 0
	v_pk_mul_f32 v[140:141], v[106:107], v[140:141]
	s_nop 0
	v_cvt_pk_f16_f32 v139, v140, v141
	v_or_b32_e32 v140, 16, v1
	v_mad_i64_i32 v[140:141], s[10:11], v140, s59, v[132:133]
	v_lshl_add_u64 v[140:141], v[140:141], 0, v[134:135]
	global_store_dwordx4 v[140:141], v[136:139], off
	s_nop 1
	v_mul_f32_e32 v136, 0xbfb8aa3b, v92
	v_mul_f32_e32 v137, 0xbfb8aa3b, v93
	v_exp_f32_e32 v136, v136
	v_exp_f32_e32 v137, v137
	v_add_f32_e32 v136, 1.0, v136
	v_add_f32_e32 v137, 1.0, v137
	v_rcp_f32_e32 v136, v136
	v_rcp_f32_e32 v137, v137
	s_nop 0
	v_pk_mul_f32 v[136:137], v[92:93], v[136:137]
	s_nop 0
	v_pk_mul_f32 v[136:137], v[84:85], v[136:137]
	s_nop 0
	v_cvt_pk_f16_f32 v136, v136, v137
	v_mul_f32_e32 v137, 0xbfb8aa3b, v94
	v_exp_f32_e32 v137, v137
	s_nop 0
	v_add_f32_e32 v137, 1.0, v137
	v_rcp_f32_e32 v138, v137
	v_mul_f32_e32 v137, 0xbfb8aa3b, v95
	v_exp_f32_e32 v137, v137
	s_nop 0
	v_add_f32_e32 v137, 1.0, v137
	v_rcp_f32_e32 v139, v137
	s_nop 0
	v_pk_mul_f32 v[138:139], v[94:95], v[138:139]
	s_nop 0
	v_pk_mul_f32 v[138:139], v[86:87], v[138:139]
	s_nop 0
	v_cvt_pk_f16_f32 v137, v138, v139
	v_mul_f32_e32 v138, 0xbfb8aa3b, v96
	v_mul_f32_e32 v139, 0xbfb8aa3b, v97
	v_exp_f32_e32 v138, v138
	v_exp_f32_e32 v139, v139
	v_add_f32_e32 v138, 1.0, v138
	v_add_f32_e32 v139, 1.0, v139
	v_rcp_f32_e32 v138, v138
	v_rcp_f32_e32 v139, v139
	s_nop 0
	v_pk_mul_f32 v[138:139], v[96:97], v[138:139]
	s_nop 0
	v_pk_mul_f32 v[138:139], v[88:89], v[138:139]
	s_nop 0
	v_cvt_pk_f16_f32 v138, v138, v139
	v_mul_f32_e32 v139, 0xbfb8aa3b, v98
	v_exp_f32_e32 v139, v139
	s_nop 0
	v_add_f32_e32 v139, 1.0, v139
	v_rcp_f32_e32 v140, v139
	v_mul_f32_e32 v139, 0xbfb8aa3b, v99
	v_exp_f32_e32 v139, v139
	s_nop 0
	v_add_f32_e32 v139, 1.0, v139
	v_rcp_f32_e32 v141, v139
	s_nop 0
	v_pk_mul_f32 v[140:141], v[98:99], v[140:141]
	s_nop 0
	v_pk_mul_f32 v[140:141], v[90:91], v[140:141]
	s_nop 0
	v_cvt_pk_f16_f32 v139, v140, v141
	v_or_b32_e32 v140, 32, v1
	v_mad_i64_i32 v[140:141], s[10:11], v140, s59, v[132:133]
	v_lshl_add_u64 v[140:141], v[140:141], 0, v[134:135]
	global_store_dwordx4 v[140:141], v[136:139], off
	s_nop 1
	v_mul_f32_e32 v136, 0xbfb8aa3b, v76
	v_mul_f32_e32 v137, 0xbfb8aa3b, v77
	v_exp_f32_e32 v136, v136
	v_exp_f32_e32 v137, v137
	v_add_f32_e32 v136, 1.0, v136
	v_add_f32_e32 v137, 1.0, v137
	v_rcp_f32_e32 v136, v136
	v_rcp_f32_e32 v137, v137
	s_nop 0
	v_pk_mul_f32 v[136:137], v[76:77], v[136:137]
	s_nop 0
	v_pk_mul_f32 v[136:137], v[68:69], v[136:137]
	s_nop 0
	v_cvt_pk_f16_f32 v136, v136, v137
	v_mul_f32_e32 v137, 0xbfb8aa3b, v78
	v_exp_f32_e32 v137, v137
	s_nop 0
	v_add_f32_e32 v137, 1.0, v137
	v_rcp_f32_e32 v138, v137
	v_mul_f32_e32 v137, 0xbfb8aa3b, v79
	v_exp_f32_e32 v137, v137
	s_nop 0
	v_add_f32_e32 v137, 1.0, v137
	v_rcp_f32_e32 v139, v137
	s_nop 0
	v_pk_mul_f32 v[138:139], v[78:79], v[138:139]
	s_nop 0
	v_pk_mul_f32 v[138:139], v[70:71], v[138:139]
	s_nop 0
	v_cvt_pk_f16_f32 v137, v138, v139
	v_mul_f32_e32 v138, 0xbfb8aa3b, v80
	v_mul_f32_e32 v139, 0xbfb8aa3b, v81
	v_exp_f32_e32 v138, v138
	v_exp_f32_e32 v139, v139
	v_add_f32_e32 v138, 1.0, v138
	v_add_f32_e32 v139, 1.0, v139
	v_rcp_f32_e32 v138, v138
	v_rcp_f32_e32 v139, v139
	s_nop 0
	v_pk_mul_f32 v[138:139], v[80:81], v[138:139]
	s_nop 0
	v_pk_mul_f32 v[138:139], v[72:73], v[138:139]
	s_nop 0
	v_cvt_pk_f16_f32 v138, v138, v139
	v_mul_f32_e32 v139, 0xbfb8aa3b, v82
	v_exp_f32_e32 v139, v139
	s_nop 0
	v_add_f32_e32 v139, 1.0, v139
	v_rcp_f32_e32 v140, v139
	v_mul_f32_e32 v139, 0xbfb8aa3b, v83
	v_exp_f32_e32 v139, v139
	s_nop 0
	v_add_f32_e32 v139, 1.0, v139
	v_rcp_f32_e32 v141, v139
	s_nop 0
	v_pk_mul_f32 v[140:141], v[82:83], v[140:141]
	s_nop 0
	v_pk_mul_f32 v[140:141], v[74:75], v[140:141]
	s_nop 0
	v_cvt_pk_f16_f32 v139, v140, v141
	v_or_b32_e32 v140, 48, v1
	v_mad_i64_i32 v[140:141], s[10:11], v140, s59, v[132:133]
	v_lshl_add_u64 v[140:141], v[140:141], 0, v[134:135]
	global_store_dwordx4 v[140:141], v[136:139], off
	s_nop 1
	v_mul_f32_e32 v136, 0xbfb8aa3b, v60
	v_mul_f32_e32 v137, 0xbfb8aa3b, v61
	v_exp_f32_e32 v136, v136
	v_exp_f32_e32 v137, v137
	v_add_f32_e32 v136, 1.0, v136
	v_add_f32_e32 v137, 1.0, v137
	v_rcp_f32_e32 v136, v136
	v_rcp_f32_e32 v137, v137
	s_nop 0
	v_pk_mul_f32 v[136:137], v[60:61], v[136:137]
	s_nop 0
	v_pk_mul_f32 v[136:137], v[52:53], v[136:137]
	s_nop 0
	v_cvt_pk_f16_f32 v136, v136, v137
	v_mul_f32_e32 v137, 0xbfb8aa3b, v62
	v_exp_f32_e32 v137, v137
	s_nop 0
	v_add_f32_e32 v137, 1.0, v137
	v_rcp_f32_e32 v138, v137
	v_mul_f32_e32 v137, 0xbfb8aa3b, v63
	v_exp_f32_e32 v137, v137
	s_nop 0
	v_add_f32_e32 v137, 1.0, v137
	v_rcp_f32_e32 v139, v137
	s_nop 0
	v_pk_mul_f32 v[138:139], v[62:63], v[138:139]
	s_nop 0
	v_pk_mul_f32 v[138:139], v[54:55], v[138:139]
	s_nop 0
	v_cvt_pk_f16_f32 v137, v138, v139
	v_mul_f32_e32 v138, 0xbfb8aa3b, v64
	v_mul_f32_e32 v139, 0xbfb8aa3b, v65
	v_exp_f32_e32 v138, v138
	v_exp_f32_e32 v139, v139
	v_add_f32_e32 v138, 1.0, v138
	v_add_f32_e32 v139, 1.0, v139
	v_rcp_f32_e32 v138, v138
	v_rcp_f32_e32 v139, v139
	s_nop 0
	v_pk_mul_f32 v[138:139], v[64:65], v[138:139]
	s_nop 0
	v_pk_mul_f32 v[138:139], v[56:57], v[138:139]
	s_nop 0
	v_cvt_pk_f16_f32 v138, v138, v139
	v_mul_f32_e32 v139, 0xbfb8aa3b, v66
	v_exp_f32_e32 v139, v139
	s_nop 0
	v_add_f32_e32 v139, 1.0, v139
	v_rcp_f32_e32 v140, v139
	v_mul_f32_e32 v139, 0xbfb8aa3b, v67
	v_exp_f32_e32 v139, v139
	s_nop 0
	v_add_f32_e32 v139, 1.0, v139
	v_rcp_f32_e32 v141, v139
	s_nop 0
	v_pk_mul_f32 v[140:141], v[66:67], v[140:141]
	s_nop 0
	v_pk_mul_f32 v[140:141], v[58:59], v[140:141]
	s_nop 0
	v_cvt_pk_f16_f32 v139, v140, v141
	v_mad_i64_i32 v[140:141], s[10:11], v142, s59, v[132:133]
	v_lshl_add_u64 v[140:141], v[140:141], 0, v[134:135]
	global_store_dwordx4 v[140:141], v[136:139], off
	s_nop 1
	v_mul_f32_e32 v136, 0xbfb8aa3b, v44
	v_mul_f32_e32 v137, 0xbfb8aa3b, v45
	v_exp_f32_e32 v136, v136
	v_exp_f32_e32 v137, v137
	v_add_f32_e32 v136, 1.0, v136
	v_add_f32_e32 v137, 1.0, v137
	v_rcp_f32_e32 v136, v136
	v_rcp_f32_e32 v137, v137
	s_nop 0
	v_pk_mul_f32 v[136:137], v[44:45], v[136:137]
	s_nop 0
	v_pk_mul_f32 v[136:137], v[36:37], v[136:137]
	s_nop 0
	v_cvt_pk_f16_f32 v136, v136, v137
	v_mul_f32_e32 v137, 0xbfb8aa3b, v46
	v_exp_f32_e32 v137, v137
	s_nop 0
	v_add_f32_e32 v137, 1.0, v137
	v_rcp_f32_e32 v138, v137
	v_mul_f32_e32 v137, 0xbfb8aa3b, v47
	v_exp_f32_e32 v137, v137
	s_nop 0
	v_add_f32_e32 v137, 1.0, v137
	v_rcp_f32_e32 v139, v137
	s_nop 0
	v_pk_mul_f32 v[138:139], v[46:47], v[138:139]
	s_nop 0
	v_pk_mul_f32 v[138:139], v[38:39], v[138:139]
	s_nop 0
	v_cvt_pk_f16_f32 v137, v138, v139
	v_mul_f32_e32 v138, 0xbfb8aa3b, v48
	v_mul_f32_e32 v139, 0xbfb8aa3b, v49
	v_exp_f32_e32 v138, v138
	v_exp_f32_e32 v139, v139
	v_add_f32_e32 v138, 1.0, v138
	v_add_f32_e32 v139, 1.0, v139
	v_rcp_f32_e32 v138, v138
	v_rcp_f32_e32 v139, v139
	s_nop 0
	v_pk_mul_f32 v[138:139], v[48:49], v[138:139]
	s_nop 0
	v_pk_mul_f32 v[138:139], v[40:41], v[138:139]
	s_nop 0
	v_cvt_pk_f16_f32 v138, v138, v139
	v_mul_f32_e32 v139, 0xbfb8aa3b, v50
	v_exp_f32_e32 v139, v139
	s_nop 0
	v_add_f32_e32 v139, 1.0, v139
	v_rcp_f32_e32 v140, v139
	v_mul_f32_e32 v139, 0xbfb8aa3b, v51
	v_exp_f32_e32 v139, v139
	s_nop 0
	v_add_f32_e32 v139, 1.0, v139
	v_rcp_f32_e32 v141, v139
	s_nop 0
	v_pk_mul_f32 v[140:141], v[50:51], v[140:141]
	s_nop 0
	v_pk_mul_f32 v[140:141], v[42:43], v[140:141]
	s_nop 0
	v_cvt_pk_f16_f32 v139, v140, v141
	v_add_u32_e32 v140, 0x90, v1
	v_mad_i64_i32 v[140:141], s[10:11], v140, s59, v[132:133]
	v_lshl_add_u64 v[140:141], v[140:141], 0, v[134:135]
	global_store_dwordx4 v[140:141], v[136:139], off
	s_nop 1
	v_mul_f32_e32 v136, 0xbfb8aa3b, v28
	v_mul_f32_e32 v137, 0xbfb8aa3b, v29
	v_exp_f32_e32 v136, v136
	v_exp_f32_e32 v137, v137
	v_add_f32_e32 v136, 1.0, v136
	v_add_f32_e32 v137, 1.0, v137
	v_rcp_f32_e32 v136, v136
	v_rcp_f32_e32 v137, v137
	s_nop 0
	v_pk_mul_f32 v[136:137], v[28:29], v[136:137]
	s_nop 0
	v_pk_mul_f32 v[136:137], v[20:21], v[136:137]
	s_nop 0
	v_cvt_pk_f16_f32 v136, v136, v137
	v_mul_f32_e32 v137, 0xbfb8aa3b, v30
	v_exp_f32_e32 v137, v137
	s_nop 0
	v_add_f32_e32 v137, 1.0, v137
	v_rcp_f32_e32 v138, v137
	v_mul_f32_e32 v137, 0xbfb8aa3b, v31
	v_exp_f32_e32 v137, v137
	s_nop 0
	v_add_f32_e32 v137, 1.0, v137
	v_rcp_f32_e32 v139, v137
	s_nop 0
	v_pk_mul_f32 v[138:139], v[30:31], v[138:139]
	s_nop 0
	v_pk_mul_f32 v[138:139], v[22:23], v[138:139]
	s_nop 0
	v_cvt_pk_f16_f32 v137, v138, v139
	v_mul_f32_e32 v138, 0xbfb8aa3b, v32
	v_mul_f32_e32 v139, 0xbfb8aa3b, v33
	v_exp_f32_e32 v138, v138
	v_exp_f32_e32 v139, v139
	v_add_f32_e32 v138, 1.0, v138
	v_add_f32_e32 v139, 1.0, v139
	v_rcp_f32_e32 v138, v138
	v_rcp_f32_e32 v139, v139
	s_nop 0
	v_pk_mul_f32 v[138:139], v[32:33], v[138:139]
	s_nop 0
	v_pk_mul_f32 v[138:139], v[24:25], v[138:139]
	s_nop 0
	v_cvt_pk_f16_f32 v138, v138, v139
	v_mul_f32_e32 v139, 0xbfb8aa3b, v34
	v_exp_f32_e32 v139, v139
	s_nop 0
	v_add_f32_e32 v139, 1.0, v139
	v_rcp_f32_e32 v140, v139
	v_mul_f32_e32 v139, 0xbfb8aa3b, v35
	v_exp_f32_e32 v139, v139
	s_nop 0
	v_add_f32_e32 v139, 1.0, v139
	v_rcp_f32_e32 v141, v139
	s_nop 0
	v_pk_mul_f32 v[140:141], v[34:35], v[140:141]
	s_nop 0
	v_pk_mul_f32 v[140:141], v[26:27], v[140:141]
	s_nop 0
	v_cvt_pk_f16_f32 v139, v140, v141
	v_add_u32_e32 v140, 0xa0, v1
	v_mad_i64_i32 v[140:141], s[10:11], v140, s59, v[132:133]
	v_lshl_add_u64 v[140:141], v[140:141], 0, v[134:135]
	global_store_dwordx4 v[140:141], v[136:139], off
	v_add_u32_e32 v1, 0xb0, v1
	v_mad_i64_i32 v[132:133], s[10:11], v1, s59, v[132:133]
	v_mul_f32_e32 v136, 0xbfb8aa3b, v12
	v_mul_f32_e32 v137, 0xbfb8aa3b, v13
	v_exp_f32_e32 v136, v136
	v_exp_f32_e32 v137, v137
	v_lshl_add_u64 v[132:133], v[132:133], 0, v[134:135]
	s_mov_b64 s[10:11], 0
	v_add_f32_e32 v136, 1.0, v136
	v_add_f32_e32 v137, 1.0, v137
	v_rcp_f32_e32 v136, v136
	v_rcp_f32_e32 v137, v137
	s_nop 0
	v_pk_mul_f32 v[136:137], v[12:13], v[136:137]
	s_nop 0
	v_pk_mul_f32 v[136:137], v[8:9], v[136:137]
	s_nop 0
	v_cvt_pk_f16_f32 v136, v136, v137
	v_mul_f32_e32 v137, 0xbfb8aa3b, v14
	v_exp_f32_e32 v137, v137
	s_nop 0
	v_add_f32_e32 v137, 1.0, v137
	v_rcp_f32_e32 v138, v137
	v_mul_f32_e32 v137, 0xbfb8aa3b, v15
	v_exp_f32_e32 v137, v137
	s_nop 0
	v_add_f32_e32 v137, 1.0, v137
	v_rcp_f32_e32 v139, v137
	s_nop 0
	v_pk_mul_f32 v[138:139], v[14:15], v[138:139]
	s_nop 0
	v_pk_mul_f32 v[138:139], v[10:11], v[138:139]
	s_nop 0
	v_cvt_pk_f16_f32 v137, v138, v139
	v_mul_f32_e32 v138, 0xbfb8aa3b, v16
	v_mul_f32_e32 v139, 0xbfb8aa3b, v17
	v_exp_f32_e32 v138, v138
	v_exp_f32_e32 v139, v139
	v_add_f32_e32 v138, 1.0, v138
	v_add_f32_e32 v139, 1.0, v139
	v_rcp_f32_e32 v138, v138
	v_rcp_f32_e32 v139, v139
	s_nop 0
	v_pk_mul_f32 v[138:139], v[16:17], v[138:139]
	s_nop 0
	v_pk_mul_f32 v[138:139], v[4:5], v[138:139]
	s_nop 0
	v_cvt_pk_f16_f32 v138, v138, v139
	v_mul_f32_e32 v139, 0xbfb8aa3b, v18
	v_exp_f32_e32 v139, v139
	s_nop 0
	v_add_f32_e32 v139, 1.0, v139
	v_rcp_f32_e32 v140, v139
	v_mul_f32_e32 v139, 0xbfb8aa3b, v19
	v_exp_f32_e32 v139, v139
	s_nop 0
	v_add_f32_e32 v139, 1.0, v139
	v_rcp_f32_e32 v141, v139
	s_nop 0
	v_pk_mul_f32 v[140:141], v[18:19], v[140:141]
	s_nop 0
	v_pk_mul_f32 v[140:141], v[6:7], v[140:141]
	s_nop 0
	v_cvt_pk_f16_f32 v139, v140, v141
	global_store_dwordx4 v[132:133], v[136:139], off
